# SSD chunk epilogue: row-sum reduction over the four 16-lane rows via v_permlane16/32_swap instead of two dependent ds_bpermute round trips
# speedup vs baseline: 1.0056x; 1.0056x over previous
.LBB0_360:
	v_add_u32_e32 v156, v106, v107
	ds_read_b128 v[160:163], v156 offset:34816
	ds_read_b128 v[164:167], v156 offset:34880
	ds_read_b128 v[168:171], v156 offset:17408
	ds_read_b128 v[172:175], v156 offset:17472
	ds_read_b128 v[176:179], v138
	ds_read_b128 v[180:183], v138 offset:64
	ds_read_b128 v[184:187], v138 offset:4352
	ds_read_b128 v[188:191], v138 offset:4416
	ds_read_b128 v[192:195], v156 offset:34944
	ds_read_b128 v[202:205], v156 offset:35008
	ds_read_b128 v[206:209], v156 offset:17536
	ds_read_b128 v[210:213], v156 offset:17600
	ds_read_b128 v[214:217], v138 offset:128
	ds_read_b128 v[236:239], v138 offset:192
	ds_read_b128 v[240:243], v138 offset:4480
	ds_read_b128 v[244:247], v138 offset:4544
	s_waitcnt lgkmcnt(11)
	v_mfma_f32_16x16x32_bf16 v[248:251], v[160:163], v[176:179], 0
	v_mfma_f32_16x16x32_bf16 v[176:179], v[168:171], v[176:179], 0
	s_waitcnt lgkmcnt(9)
	v_mfma_f32_16x16x32_bf16 v[160:163], v[160:163], v[184:187], 0
	v_mfma_f32_16x16x32_bf16 v[168:171], v[168:171], v[184:187], 0
	v_mfma_f32_16x16x32_bf16 v[184:187], v[164:167], v[180:183], v[248:251]
	v_mfma_f32_16x16x32_bf16 v[176:179], v[172:175], v[180:183], v[176:179]
	s_waitcnt lgkmcnt(8)
	v_mfma_f32_16x16x32_bf16 v[160:163], v[164:167], v[188:191], v[160:163]
	v_mfma_f32_16x16x32_bf16 v[164:167], v[172:175], v[188:191], v[168:171]
	s_waitcnt lgkmcnt(3)
	v_mfma_f32_16x16x32_bf16 v[168:171], v[192:195], v[214:217], v[184:187]
	v_mfma_f32_16x16x32_bf16 v[172:175], v[206:209], v[214:217], v[176:179]
	s_waitcnt lgkmcnt(1)
	v_mfma_f32_16x16x32_bf16 v[160:163], v[192:195], v[240:243], v[160:163]
	s_nop 0
	ds_read_b128 v[176:179], v139
	ds_read_b128 v[180:183], v140 offset:52224
	ds_read_b128 v[184:187], v141 offset:54528
	ds_read_b128 v[188:191], v142 offset:56832
	ds_read_b128 v[192:195], v143 offset:59136
	v_mfma_f32_16x16x32_bf16 v[164:167], v[206:209], v[240:243], v[164:167]
	s_waitcnt lgkmcnt(5)
	v_mfma_f32_16x16x32_bf16 v[160:163], v[202:205], v[244:247], v[160:163]
	v_mfma_f32_16x16x32_bf16 v[168:171], v[202:205], v[236:239], v[168:171]
	v_mfma_f32_16x16x32_bf16 v[172:175], v[210:213], v[236:239], v[172:175]
	v_mfma_f32_16x16x32_bf16 v[164:167], v[210:213], v[244:247], v[164:167]
	ds_read_b32 v55, v109
	ds_read_b128 v[202:205], v127
	s_waitcnt lgkmcnt(0)
	v_sub_f32_e32 v89, v55, v202
	v_sub_f32_e32 v153, v55, v203
	v_sub_f32_e32 v154, v55, v204
	v_sub_f32_e32 v157, v55, v205
	v_mul_f32_e32 v89, 0x3fb8aa3b, v89
	v_mul_f32_e32 v153, 0x3fb8aa3b, v153
	v_mul_f32_e32 v154, 0x3fb8aa3b, v154
	v_mul_f32_e32 v157, 0x3fb8aa3b, v157
	v_exp_f32_e32 v89, v89
	v_exp_f32_e32 v153, v153
	v_exp_f32_e32 v154, v154
	v_exp_f32_e32 v157, v157
	v_mul_f32_e32 v89, v172, v89
	v_mul_f32_e32 v153, v173, v153
	v_mul_f32_e32 v154, v174, v154
	v_mul_f32_e32 v157, v175, v157
	v_cndmask_b32_e64 v89, v89, 0, s[42:43]
	v_cndmask_b32_e64 v153, 0, v153, s[44:45]
	v_cndmask_b32_e64 v154, v154, 0, s[46:47]
	v_cndmask_b32_e64 v157, v157, 0, s[48:49]
	v_cvt_pk_bf16_f32 v172, v89, v153
	v_cvt_pk_bf16_f32 v173, v154, v157
	ds_write_b64 v144, v[172:173]
	ds_read_b32 v89, v110
	ds_read_b128 v[172:175], v127
	v_mul_f32_e32 v55, 0x3fb8aa3b, v55
	v_exp_f32_e32 v154, v55
	s_waitcnt lgkmcnt(1)
	v_mul_f32_e32 v55, 0x3fb8aa3b, v89
	s_waitcnt lgkmcnt(0)
	v_sub_f32_e32 v153, v89, v172
	v_sub_f32_e32 v157, v89, v173
	v_mul_f32_e32 v153, 0x3fb8aa3b, v153
	v_mul_f32_e32 v157, 0x3fb8aa3b, v157
	v_exp_f32_e32 v153, v153
	v_exp_f32_e32 v157, v157
	v_exp_f32_e32 v206, v55
	v_mul_f32_e32 v55, v164, v153
	v_mul_f32_e32 v153, v165, v157
	v_sub_f32_e32 v157, v89, v174
	v_sub_f32_e32 v89, v89, v175
	v_mul_f32_e32 v157, 0x3fb8aa3b, v157
	v_mul_f32_e32 v89, 0x3fb8aa3b, v89
	v_exp_f32_e32 v157, v157
	v_exp_f32_e32 v89, v89
	v_cndmask_b32_e64 v55, v55, 0, s[50:51]
	v_cndmask_b32_e64 v153, 0, v153, s[52:53]
	v_mul_f32_e32 v157, v166, v157
	v_mul_f32_e32 v89, v167, v89
	v_cndmask_b32_e64 v157, v157, 0, s[54:55]
	v_cndmask_b32_e64 v89, v89, 0, s[56:57]
	v_cvt_pk_bf16_f32 v164, v55, v153
	v_cvt_pk_bf16_f32 v165, v157, v89
	ds_write_b64 v145, v[164:165]
	v_mul_f32_e32 v54, 0x3fb8aa3b, v54
	v_exp_f32_e32 v54, v54
	ds_read_b128 v[164:167], v146 offset:52224
	v_add_u32_e32 v159, v108, v111
	ds_read_b128 v[172:175], v159
	v_pk_mul_f32 v[50:51], v[50:51], v[54:55] op_sel_hi:[1,0]
	v_pk_mul_f32 v[48:49], v[48:49], v[54:55] op_sel_hi:[1,0]
	v_pk_mul_f32 v[42:43], v[42:43], v[54:55] op_sel_hi:[1,0]
	v_pk_mul_f32 v[40:41], v[40:41], v[54:55] op_sel_hi:[1,0]
	v_pk_mul_f32 v[46:47], v[46:47], v[54:55] op_sel_hi:[1,0]
	v_pk_mul_f32 v[44:45], v[44:45], v[54:55] op_sel_hi:[1,0]
	v_pk_mul_f32 v[38:39], v[38:39], v[54:55] op_sel_hi:[1,0]
	v_pk_mul_f32 v[36:37], v[36:37], v[54:55] op_sel_hi:[1,0]
	v_mfma_f32_16x16x32_bf16 v[48:51], v[180:183], v[176:179], v[48:51]
	v_add_u32_e32 v54, v112, v113
	v_mfma_f32_16x16x32_bf16 v[40:43], v[184:187], v[176:179], v[40:43]
	v_mfma_f32_16x16x32_bf16 v[44:47], v[188:191], v[176:179], v[44:47]
	v_mfma_f32_16x16x32_bf16 v[36:39], v[192:195], v[176:179], v[36:39]
	ds_read_b128 v[176:179], v147 offset:54528
	s_waitcnt lgkmcnt(1)
	v_mfma_f32_16x16x32_bf16 v[48:51], v[164:167], v[172:175], v[48:51]
	ds_read_b128 v[164:167], v148 offset:56832
	ds_read_b128 v[180:183], v149 offset:59136
	s_waitcnt lgkmcnt(0)
	s_barrier
	s_waitcnt lgkmcnt(2)
	v_mfma_f32_16x16x32_bf16 v[40:43], v[176:179], v[172:175], v[40:43]
	ds_read_b128 v[176:179], v54
	ds_read_b128 v[184:187], v150
	v_add_u32_e32 v54, v112, v111
	s_waitcnt lgkmcnt(3)
	v_mfma_f32_16x16x32_bf16 v[44:47], v[164:167], v[172:175], v[44:47]
	ds_read_b128 v[164:167], v150 offset:2304
	ds_read_b128 v[188:191], v150 offset:64
	ds_read_b128 v[192:195], v54
	ds_read_b128 v[202:205], v150 offset:2368
	s_waitcnt lgkmcnt(6)
	v_mfma_f32_16x16x32_bf16 v[36:39], v[180:183], v[172:175], v[36:39]
	v_mul_f32_e64 v170, v170, v154
	v_mul_f32_e64 v171, v171, v154
	v_pk_mul_f32 v[168:169], v[168:169], v[154:155] op_sel_hi:[1,0]
	v_pk_mul_f32 v[162:163], v[162:163], v[206:207] op_sel_hi:[1,0]
	v_pk_mul_f32 v[160:161], v[160:161], v[206:207] op_sel_hi:[1,0]
	s_waitcnt lgkmcnt(4)
	v_mfma_f32_16x16x32_bf16 v[168:171], v[176:179], v[184:187], v[168:171]
	v_cvt_pk_bf16_f32 v54, v48, v49
	v_cvt_pk_bf16_f32 v55, v50, v51
	v_cvt_pk_bf16_f32 v172, v40, v41
	v_cvt_pk_bf16_f32 v173, v42, v43
	v_add_u32_e32 v157, 0x8800, v151
	s_waitcnt lgkmcnt(3)
	v_mfma_f32_16x16x32_bf16 v[160:163], v[176:179], v[164:167], v[160:163]
	ds_write2_b64 v157, v[54:55], v[172:173] offset1:4
	v_cvt_pk_bf16_f32 v54, v44, v45
	v_cvt_pk_bf16_f32 v55, v46, v47
	s_waitcnt lgkmcnt(2)
	v_mfma_f32_16x16x32_bf16 v[164:167], v[192:195], v[188:191], v[168:171]
	v_cmp_lt_i32_e32 vcc, v225, v220
	v_lshl_add_u64 v[92:93], v[86:87], 0, v[92:93]
	s_nop 0
	v_cvt_pk_bf16_f32 v168, v36, v37
	v_cvt_pk_bf16_f32 v169, v38, v39
	ds_write2_b64 v157, v[54:55], v[168:169] offset0:8 offset1:12
	v_cndmask_b32_e32 v54, v218, v225, vcc
	v_lshlrev_b32_e32 v153, 2, v54
	s_waitcnt vmcnt(9)
	v_lshlrev_b32_e32 v54, 16, v52
	v_and_b32_e32 v55, 0xffff0000, v52
	v_mul_f32_e32 v52, 0xbfb8aa3b, v54
	v_exp_f32_e32 v52, v52
	v_mul_f32_e32 v89, 0xbfb8aa3b, v55
	v_exp_f32_e32 v89, v89
	ds_read_b64 v[168:169], v128
	v_add_f32_e32 v52, 1.0, v52
	v_rcp_f32_e32 v170, v52
	v_add_f32_e32 v52, 1.0, v89
	v_rcp_f32_e32 v171, v52
	s_waitcnt lgkmcnt(0)
	v_lshlrev_b32_e32 v172, 16, v168
	v_and_b32_e32 v173, 0xffff0000, v168
	v_pk_fma_f32 v[164:165], v[0:1], v[172:173], v[164:165]
	v_pk_mul_f32 v[54:55], v[170:171], v[54:55]
	v_lshlrev_b32_e32 v52, 16, v53
	v_pk_mul_f32 v[164:165], v[54:55], v[164:165]
	v_and_b32_e32 v53, 0xffff0000, v53
	v_mul_f32_e32 v54, 0xbfb8aa3b, v52
	v_exp_f32_e32 v89, v54
	v_mul_f32_e32 v54, 0xbfb8aa3b, v53
	v_exp_f32_e32 v154, v54
	v_lshlrev_b32_e32 v168, 16, v169
	v_add_f32_e32 v89, 1.0, v89
	v_rcp_f32_e32 v170, v89
	v_add_f32_e32 v89, 1.0, v154
	v_rcp_f32_e32 v171, v89
	v_and_b32_e32 v169, 0xffff0000, v169
	v_pk_fma_f32 v[166:167], v[0:1], v[168:169], v[166:167]
	v_pk_mul_f32 v[54:55], v[164:165], v[164:165]
	v_pk_mul_f32 v[52:53], v[170:171], v[52:53]
	v_add_f32_e32 v54, v54, v55
	v_pk_mul_f32 v[166:167], v[52:53], v[166:167]
	v_cmp_lt_i32_e32 vcc, v226, v220
	v_pk_mul_f32 v[52:53], v[166:167], v[166:167]
	s_nop 0
	v_add_f32_e32 v52, v52, v54
	v_add_f32_e32 v89, v53, v52
	v_mov_b32_e32 v168, v89
	v_cndmask_b32_e32 v154, v218, v226, vcc
	v_lshlrev_b32_e32 v154, 2, v154
	v_mfma_f32_16x16x32_bf16 v[52:55], v[192:195], v[202:205], v[160:163]
	s_nop 1
	v_permlane16_swap_b32_e32 v89, v168
	v_add_f32_e32 v89, v89, v168
	v_mov_b32_e32 v168, v89
	s_nop 1
	v_permlane32_swap_b32_e32 v89, v168
	v_cvt_pk_bf16_f32 v162, v164, v165
	v_cvt_pk_bf16_f32 v163, v166, v167
	global_store_dwordx2 v[92:93], v[162:163], off
	s_and_saveexec_b64 s[0:1], s[58:59]
	s_cbranch_execz .LBB0_362
	v_add_f32_e32 v89, v89, v168
	ds_write_b32 v114, v89
.LBB0_362:
	s_or_b64 exec, exec, s[0:1]
	s_waitcnt vmcnt(9)
	v_lshlrev_b32_e32 v162, 16, v84
	v_and_b32_e32 v163, 0xffff0000, v84
	v_mul_f32_e32 v84, 0xbfb8aa3b, v162
	v_exp_f32_e32 v84, v84
	ds_read_b64 v[92:93], v129
	v_add_f32_e32 v84, 1.0, v84
	v_rcp_f32_e32 v164, v84
	v_mul_f32_e32 v84, 0xbfb8aa3b, v163
	v_exp_f32_e32 v84, v84
	s_waitcnt lgkmcnt(0)
	v_lshlrev_b32_e32 v160, 16, v92
	v_and_b32_e32 v161, 0xffff0000, v92
	v_pk_fma_f32 v[52:53], v[0:1], v[160:161], v[52:53]
	v_add_f32_e32 v84, 1.0, v84
	v_rcp_f32_e32 v165, v84
	v_lshlrev_b32_e32 v84, 16, v85
	v_mul_f32_e32 v89, 0xbfb8aa3b, v84
	v_exp_f32_e32 v89, v89
	v_and_b32_e32 v85, 0xffff0000, v85
	v_pk_mul_f32 v[160:161], v[164:165], v[162:163]
	v_lshlrev_b32_e32 v92, 16, v93
	v_add_f32_e32 v89, 1.0, v89
	v_rcp_f32_e32 v162, v89
	v_mul_f32_e32 v89, 0xbfb8aa3b, v85
	v_exp_f32_e32 v89, v89
	v_and_b32_e32 v93, 0xffff0000, v93
	v_pk_mul_f32 v[52:53], v[160:161], v[52:53]
	v_pk_fma_f32 v[54:55], v[0:1], v[92:93], v[54:55]
	v_add_f32_e32 v89, 1.0, v89
	v_rcp_f32_e32 v163, v89
	v_pk_mul_f32 v[160:161], v[52:53], v[52:53]
	v_cvt_pk_bf16_f32 v52, v52, v53
	v_add_f32_e32 v89, v160, v161
	v_pk_mul_f32 v[84:85], v[162:163], v[84:85]
	s_nop 0
	v_pk_mul_f32 v[54:55], v[84:85], v[54:55]
	s_nop 0
	v_pk_mul_f32 v[84:85], v[54:55], v[54:55]
	v_cvt_pk_bf16_f32 v53, v54, v55
	v_add_f32_e32 v84, v84, v89
	v_add_f32_e32 v84, v85, v84
	v_lshl_add_u64 v[54:55], v[86:87], 0, v[90:91]
	global_store_dwordx2 v[54:55], v[52:53], off
	v_mov_b32_e32 v52, v84
	s_nop 1
	v_permlane16_swap_b32_e32 v84, v52
	v_add_f32_e32 v52, v84, v52
	v_mov_b32_e32 v53, v52
	s_nop 1
	v_permlane32_swap_b32_e32 v52, v53
	s_and_saveexec_b64 s[0:1], s[58:59]
	s_cbranch_execz .LBB0_364
	v_add_f32_e32 v52, v52, v53
	ds_write_b32 v114, v52 offset:64

.LBB0_373:
	ds_read_b128 v[160:163], v156 offset:34816
	ds_read_b128 v[164:167], v156 offset:34880
	ds_read_b128 v[168:171], v156 offset:17408
	ds_read_b128 v[172:175], v156 offset:17472
	ds_read_b128 v[176:179], v138
	ds_read_b128 v[180:183], v138 offset:64
	ds_read_b128 v[184:187], v138 offset:4352
	ds_read_b128 v[188:191], v138 offset:4416
	ds_read_b128 v[192:195], v156 offset:34944
	ds_read_b128 v[202:205], v156 offset:35008
	ds_read_b128 v[206:209], v156 offset:17536
	ds_read_b128 v[210:213], v156 offset:17600
	ds_read_b128 v[214:217], v138 offset:128
	ds_read_b128 v[236:239], v138 offset:192
	ds_read_b128 v[240:243], v138 offset:4480
	ds_read_b128 v[244:247], v138 offset:4544
	s_waitcnt lgkmcnt(11)
	v_mfma_f32_16x16x32_bf16 v[248:251], v[160:163], v[176:179], 0
	v_mfma_f32_16x16x32_bf16 v[176:179], v[168:171], v[176:179], 0
	s_waitcnt lgkmcnt(9)
	v_mfma_f32_16x16x32_bf16 v[160:163], v[160:163], v[184:187], 0
	v_mfma_f32_16x16x32_bf16 v[168:171], v[168:171], v[184:187], 0
	v_mfma_f32_16x16x32_bf16 v[184:187], v[164:167], v[180:183], v[248:251]
	v_mfma_f32_16x16x32_bf16 v[176:179], v[172:175], v[180:183], v[176:179]
	s_waitcnt lgkmcnt(8)
	v_mfma_f32_16x16x32_bf16 v[160:163], v[164:167], v[188:191], v[160:163]
	v_mfma_f32_16x16x32_bf16 v[164:167], v[172:175], v[188:191], v[168:171]
	s_waitcnt lgkmcnt(3)
	v_mfma_f32_16x16x32_bf16 v[168:171], v[192:195], v[214:217], v[184:187]
	v_mfma_f32_16x16x32_bf16 v[172:175], v[206:209], v[214:217], v[176:179]
	s_waitcnt lgkmcnt(1)
	v_mfma_f32_16x16x32_bf16 v[160:163], v[192:195], v[240:243], v[160:163]
	s_nop 0
	ds_read_b128 v[176:179], v139
	ds_read_b128 v[180:183], v140 offset:52224
	ds_read_b128 v[184:187], v141 offset:54528
	ds_read_b128 v[188:191], v142 offset:56832
	ds_read_b128 v[192:195], v143 offset:59136
	v_mfma_f32_16x16x32_bf16 v[164:167], v[206:209], v[240:243], v[164:167]
	v_mfma_f32_16x16x32_bf16 v[168:171], v[202:205], v[236:239], v[168:171]
	v_mfma_f32_16x16x32_bf16 v[172:175], v[210:213], v[236:239], v[172:175]
	s_waitcnt lgkmcnt(5)
	v_mfma_f32_16x16x32_bf16 v[160:163], v[202:205], v[244:247], v[160:163]
	v_mfma_f32_16x16x32_bf16 v[164:167], v[210:213], v[244:247], v[164:167]
	ds_read_b32 v88, v120
	ds_read_b128 v[202:205], v131
	s_waitcnt lgkmcnt(0)
	v_sub_f32_e32 v54, v88, v202
	v_sub_f32_e32 v55, v88, v203
	v_sub_f32_e32 v89, v88, v204
	s_waitcnt vmcnt(19)
	v_sub_f32_e32 v152, v88, v205
	v_mul_f32_e32 v54, 0x3fb8aa3b, v54
	v_mul_f32_e32 v55, 0x3fb8aa3b, v55
	v_mul_f32_e32 v89, 0x3fb8aa3b, v89
	v_mul_f32_e32 v152, 0x3fb8aa3b, v152
	v_exp_f32_e32 v54, v54
	v_exp_f32_e32 v55, v55
	v_exp_f32_e32 v89, v89
	v_exp_f32_e32 v152, v152
	v_mul_f32_e32 v54, v172, v54
	v_mul_f32_e32 v55, v173, v55
	v_mul_f32_e32 v89, v174, v89
	v_mul_f32_e32 v152, v175, v152
	v_cndmask_b32_e64 v54, v54, 0, s[42:43]
	v_cndmask_b32_e64 v55, 0, v55, s[44:45]
	v_cndmask_b32_e64 v89, v89, 0, s[46:47]
	v_cndmask_b32_e64 v152, v152, 0, s[48:49]
	v_cvt_pk_bf16_f32 v54, v54, v55
	v_cvt_pk_bf16_f32 v55, v89, v152
	ds_write_b64 v144, v[54:55]
	ds_read_b32 v55, v121
	ds_read_b128 v[172:175], v131
	v_mul_f32_e32 v54, 0x3fb8aa3b, v88
	v_exp_f32_e32 v54, v54
	s_waitcnt lgkmcnt(1)
	v_mul_f32_e32 v88, 0x3fb8aa3b, v55
	s_waitcnt lgkmcnt(0)
	v_sub_f32_e32 v89, v55, v172
	v_sub_f32_e32 v152, v55, v173
	v_sub_f32_e32 v155, v55, v174
	v_sub_f32_e32 v55, v55, v175
	v_mul_f32_e32 v89, 0x3fb8aa3b, v89
	v_mul_f32_e32 v152, 0x3fb8aa3b, v152
	v_mul_f32_e32 v155, 0x3fb8aa3b, v155
	v_mul_f32_e32 v55, 0x3fb8aa3b, v55
	v_exp_f32_e32 v89, v89
	v_exp_f32_e32 v152, v152
	v_exp_f32_e32 v155, v155
	v_exp_f32_e32 v55, v55
	v_exp_f32_e32 v88, v88
	v_mul_f32_e32 v89, v164, v89
	v_mul_f32_e32 v152, v165, v152
	v_mul_f32_e32 v155, v166, v155
	v_mul_f32_e32 v55, v167, v55
	v_cndmask_b32_e64 v89, v89, 0, s[50:51]
	v_cndmask_b32_e64 v152, 0, v152, s[52:53]
	v_cndmask_b32_e64 v155, v155, 0, s[54:55]
	v_cndmask_b32_e64 v55, v55, 0, s[56:57]
	v_cvt_pk_bf16_f32 v164, v89, v152
	v_cvt_pk_bf16_f32 v165, v155, v55
	ds_write_b64 v145, v[164:165]
	v_mul_f32_e32 v2, 0x3fb8aa3b, v2
	v_exp_f32_e32 v2, v2
	ds_read_b128 v[164:167], v159
	ds_read_b128 v[172:175], v146 offset:52224
	v_add_u32_e32 v55, v122, v111
	v_pk_mul_f32 v[50:51], v[50:51], v[2:3] op_sel_hi:[1,0]
	v_pk_mul_f32 v[48:49], v[48:49], v[2:3] op_sel_hi:[1,0]
	v_pk_mul_f32 v[42:43], v[42:43], v[2:3] op_sel_hi:[1,0]
	v_pk_mul_f32 v[40:41], v[40:41], v[2:3] op_sel_hi:[1,0]
	v_mfma_f32_16x16x32_bf16 v[48:51], v[180:183], v[176:179], v[48:51]
	v_mul_f32_e64 v46, v46, v2
	v_mul_f32_e64 v47, v47, v2
	v_pk_mul_f32 v[44:45], v[44:45], v[2:3] op_sel_hi:[1,0]
	v_pk_mul_f32 v[38:39], v[38:39], v[2:3] op_sel_hi:[1,0]
	v_pk_mul_f32 v[36:37], v[36:37], v[2:3] op_sel_hi:[1,0]
	v_mfma_f32_16x16x32_bf16 v[40:43], v[184:187], v[176:179], v[40:43]
	v_add_u32_e32 v2, v122, v113
	v_mfma_f32_16x16x32_bf16 v[44:47], v[188:191], v[176:179], v[44:47]
	v_mfma_f32_16x16x32_bf16 v[36:39], v[192:195], v[176:179], v[36:39]
	ds_read_b128 v[176:179], v147 offset:54528
	ds_read_b128 v[180:183], v148 offset:56832
	s_waitcnt lgkmcnt(2)
	v_mfma_f32_16x16x32_bf16 v[48:51], v[172:175], v[164:167], v[48:51]
	ds_read_b128 v[172:175], v149 offset:59136
	s_waitcnt lgkmcnt(0)
	s_barrier
	s_waitcnt lgkmcnt(2)
	v_mfma_f32_16x16x32_bf16 v[40:43], v[176:179], v[164:167], v[40:43]
	ds_read_b128 v[176:179], v2
	ds_read_b128 v[184:187], v55
	s_waitcnt lgkmcnt(3)
	v_mfma_f32_16x16x32_bf16 v[44:47], v[180:183], v[164:167], v[44:47]
	ds_read_b128 v[180:183], v150
	ds_read_b128 v[188:191], v150 offset:64
	ds_read_b128 v[192:195], v150 offset:2304
	ds_read_b128 v[202:205], v150 offset:2368
	s_waitcnt lgkmcnt(6)
	v_mfma_f32_16x16x32_bf16 v[36:39], v[172:175], v[164:167], v[36:39]
	v_mul_f32_e64 v166, v170, v54
	v_mul_f32_e64 v167, v171, v54
	v_pk_mul_f32 v[164:165], v[168:169], v[54:55] op_sel_hi:[1,0]
	v_pk_mul_f32 v[162:163], v[162:163], v[88:89] op_sel_hi:[1,0]
	v_pk_mul_f32 v[160:161], v[160:161], v[88:89] op_sel_hi:[1,0]
	v_cvt_pk_bf16_f32 v54, v48, v49
	v_cvt_pk_bf16_f32 v55, v50, v51
	v_cvt_pk_bf16_f32 v88, v40, v41
	v_cvt_pk_bf16_f32 v89, v42, v43
	ds_write2_b64 v157, v[54:55], v[88:89] offset1:4
	v_cvt_pk_bf16_f32 v54, v44, v45
	v_cvt_pk_bf16_f32 v55, v46, v47
	v_cvt_pk_bf16_f32 v88, v36, v37
	v_cvt_pk_bf16_f32 v89, v38, v39
	ds_write2_b64 v157, v[54:55], v[88:89] offset0:8 offset1:12
	s_waitcnt vmcnt(9)
	v_lshlrev_b32_e32 v54, 16, v52
	v_and_b32_e32 v55, 0xffff0000, v52
	v_mul_f32_e32 v2, 0xbfb8aa3b, v54
	v_exp_f32_e32 v2, v2
	v_mul_f32_e32 v52, 0xbfb8aa3b, v55
	v_exp_f32_e32 v52, v52
	s_waitcnt lgkmcnt(5)
	v_mfma_f32_16x16x32_bf16 v[164:167], v[176:179], v[180:183], v[164:167]
	ds_read_b64 v[88:89], v132
	v_add_f32_e32 v2, 1.0, v2
	v_rcp_f32_e32 v156, v2
	v_add_f32_e32 v2, 1.0, v52
	s_waitcnt lgkmcnt(4)
	v_mfma_f32_16x16x32_bf16 v[158:161], v[176:179], v[192:195], v[160:163]
	v_rcp_f32_e32 v157, v2
	v_lshlrev_b32_e32 v52, 16, v53
	v_and_b32_e32 v53, 0xffff0000, v53
	v_mfma_f32_16x16x32_bf16 v[162:165], v[184:187], v[188:191], v[164:167]
	v_mul_f32_e64 v54, v156, v54
	v_mul_f32_e64 v55, v157, v55
	v_mul_f32_e32 v2, 0xbfb8aa3b, v52
	v_exp_f32_e32 v2, v2
	s_waitcnt lgkmcnt(0)
	v_lshlrev_b32_e32 v166, 16, v88
	v_and_b32_e32 v167, 0xffff0000, v88
	s_nop 0
	v_pk_fma_f32 v[162:163], v[0:1], v[166:167], v[162:163]
	v_add_f32_e32 v2, 1.0, v2
	v_pk_mul_f32 v[156:157], v[54:55], v[162:163]
	v_mul_f32_e32 v54, 0xbfb8aa3b, v53
	v_exp_f32_e32 v88, v54
	v_rcp_f32_e32 v162, v2
	v_pk_mul_f32 v[54:55], v[156:157], v[156:157]
	v_cvt_pk_bf16_f32 v156, v156, v157
	v_add_f32_e32 v2, 1.0, v88
	v_rcp_f32_e32 v163, v2
	v_lshlrev_b32_e32 v88, 16, v89
	v_and_b32_e32 v89, 0xffff0000, v89
	v_pk_fma_f32 v[88:89], v[0:1], v[88:89], v[164:165]
	v_pk_mul_f32 v[52:53], v[162:163], v[52:53]
	v_add_f32_e32 v2, v54, v55
	v_pk_mul_f32 v[162:163], v[52:53], v[88:89]
	v_lshl_add_u64 v[92:93], v[86:87], 0, v[92:93]
	v_pk_mul_f32 v[52:53], v[162:163], v[162:163]
	v_cvt_pk_bf16_f32 v157, v162, v163
	v_add_f32_e32 v2, v52, v2
	v_add_f32_e32 v2, v53, v2
	v_mov_b32_e32 v88, v2
	v_mfma_f32_16x16x32_bf16 v[52:55], v[184:187], v[202:205], v[158:161]
	global_store_dwordx2 v[92:93], v[156:157], off
	s_nop 1
	v_permlane16_swap_b32_e32 v2, v88
	v_add_f32_e32 v2, v2, v88
	v_mov_b32_e32 v88, v2
	s_nop 1
	v_permlane32_swap_b32_e32 v2, v88
	s_and_saveexec_b64 s[0:1], s[58:59]
	s_cbranch_execz .LBB0_375
	v_add_f32_e32 v2, v2, v88
	ds_write_b32 v114, v2
.LBB0_375:
	s_or_b64 exec, exec, s[0:1]
	s_waitcnt vmcnt(9)
	v_lshlrev_b32_e32 v156, 16, v84
	v_mul_f32_e32 v2, 0xbfb8aa3b, v156
	v_exp_f32_e32 v2, v2
	v_and_b32_e32 v157, 0xffff0000, v84
	v_lshlrev_b32_e32 v84, 16, v85
	s_waitcnt lgkmcnt(0)
	ds_read_b64 v[88:89], v133
	v_add_f32_e32 v2, 1.0, v2
	v_rcp_f32_e32 v158, v2
	v_mul_f32_e32 v2, 0xbfb8aa3b, v157
	v_exp_f32_e32 v2, v2
	s_waitcnt lgkmcnt(0)
	v_lshlrev_b32_e32 v92, 16, v88
	v_and_b32_e32 v93, 0xffff0000, v88
	v_and_b32_e32 v85, 0xffff0000, v85
	v_add_f32_e32 v2, 1.0, v2
	v_rcp_f32_e32 v159, v2
	v_mul_f32_e32 v2, 0xbfb8aa3b, v84
	v_exp_f32_e32 v2, v2
	v_pk_fma_f32 v[52:53], v[0:1], v[92:93], v[52:53]
	v_pk_mul_f32 v[92:93], v[158:159], v[156:157]
	v_lshlrev_b32_e32 v88, 16, v89
	v_add_f32_e32 v2, 1.0, v2
	v_rcp_f32_e32 v156, v2
	v_mul_f32_e32 v2, 0xbfb8aa3b, v85
	v_exp_f32_e32 v2, v2
	v_and_b32_e32 v89, 0xffff0000, v89
	v_pk_mul_f32 v[52:53], v[92:93], v[52:53]
	v_pk_fma_f32 v[54:55], v[0:1], v[88:89], v[54:55]
	v_add_f32_e32 v2, 1.0, v2
	v_rcp_f32_e32 v157, v2
	v_pk_mul_f32 v[92:93], v[52:53], v[52:53]
	v_cvt_pk_bf16_f32 v52, v52, v53
	v_add_f32_e32 v2, v92, v93
	v_pk_mul_f32 v[84:85], v[156:157], v[84:85]
	s_nop 0
	v_pk_mul_f32 v[54:55], v[84:85], v[54:55]
	s_nop 0
	v_pk_mul_f32 v[84:85], v[54:55], v[54:55]
	v_cvt_pk_bf16_f32 v53, v54, v55
	v_add_f32_e32 v2, v84, v2
	v_add_f32_e32 v2, v85, v2
	v_lshl_add_u64 v[54:55], v[86:87], 0, v[90:91]
	global_store_dwordx2 v[54:55], v[52:53], off
	v_mov_b32_e32 v52, v2
	s_nop 1
	v_permlane16_swap_b32_e32 v2, v52
	v_add_f32_e32 v2, v2, v52
	v_mov_b32_e32 v52, v2
	s_nop 1
	v_permlane32_swap_b32_e32 v2, v52
	s_and_saveexec_b64 s[0:1], s[58:59]
	s_cbranch_execz .LBB0_350
	v_add_f32_e32 v2, v2, v52
	ds_write_b32 v114, v2 offset:64
	s_branch .LBB0_350
